# C mixer: done-flags read with two b128 loads; each sub-block's K and V fragments loaded up front
# speedup vs baseline: 1.0022x; 1.0005x over previous
; #define LAS __attribute__((address_space(3)))
; __device__ __forceinline__ f32x16 mfma32(bf16x8 a, bf16x8 b, f32x16 c) { return __builtin_amdgcn_mfma_f32_32x32x16_bf16(a, b, c, 0, 0, 0); }
; #define FRAG_LOAD(cb_) do { LOADK(kf, cb_); LOADV(vf, cb_); } while (0)
; __device__ __forceinline__ void sub_C(const LAS unsigned char* cb, const bf16x8 (&qf)[4], int kq, int h, f32x16& o0, f32x16& o1, float& carry) {
;     bf16x8 kf[4], vf[2][2]; FRAG_LOAD(cb);
;     f32x16 z = {};
; #pragma unroll
;     for (int s = 0; s < 4; ++s) z = mfma32(kf[s], qf[s], z);
; __device__ __forceinline__ void blk_C(int b, int hd, int chunk, const bf16_t* QK, const bf16_t* VT, bf16_t* mixed, LAS unsigned char* lds, int tid, int lane, int wave) {
;     ...
;         for (int u = 1; u >= 0; --u) { const int kb = 2 * sbk + u;
;             if (kb <= qb && !done) { sub_C(cb + u * 8192, qf, (kb == qb) ? q - 8 * h : 64, h, o0, o1, carry); if (__all(carry < -64.0f)) done = true; } }
.LBB0_322:
	s_add_i32 s54, s31, -2
	s_max_i32 s92, s54, 0
	s_lshl_b32 s56, s35, 14
	s_lshl_b64 s[54:55], s[92:93], 18
	v_lshl_add_u64 v[2:3], v[82:83], 0, s[54:55]
	s_add_i32 s54, s34, s56
	v_lshl_add_u64 v[2:3], v[2:3], 0, s[10:11]
	s_add_i32 m0, s54, 0x8900
	s_lshl_b32 s92, s92, 7
	global_load_lds_dwordx4 v[2:3], off
	v_lshl_add_u64 v[2:3], v[84:85], 0, s[92:93]
	s_add_i32 m0, s54, 0x9900
	s_lshl_b32 s56, s95, 14
	global_load_lds_dwordx4 v[2:3], off
	s_cmp_ge_i32 s52, s29
	s_cselect_b64 s[54:55], -1, 0
	s_or_b64 s[54:55], s[54:55], s[0:1]
	s_and_b64 vcc, exec, s[54:55]
	v_add_u32_e32 v0, s56, v179
	s_cbranch_vccnz .LBB0_324
	ds_read_b128 v[2:5], v0 offset:43264
	ds_read_b128 v[6:9], v0 offset:44288
	ds_read_b128 v[146:149], v0 offset:45312
	ds_read_b128 v[150:153], v0 offset:46336
	ds_read_b128 v[154:157], v0 offset:47360
	ds_read_b128 v[158:161], v0 offset:48384
	ds_read_b128 v[162:165], v0 offset:49408
	ds_read_b128 v[166:169], v0 offset:50432
	s_cmp_eq_u32 s27, 0
	s_cselect_b64 vcc, -1, 0
	s_waitcnt lgkmcnt(6)
	v_mfma_f32_32x32x16_bf16 v[48:63], v[2:5], v[64:67], 0
	v_mfma_f32_32x32x16_bf16 v[48:63], v[6:9], v[68:71], v[48:63]


; __device__ __forceinline__ float ex2(float x) { return __builtin_amdgcn_exp2f(x); }
; __device__ __forceinline__ float lg2(float x) { return __builtin_amdgcn_logf(x); }
; __device__ __forceinline__ f32x16 mfma32(bf16x8 a, bf16x8 b, f32x16 c) { return __builtin_amdgcn_mfma_f32_32x32x16_bf16(a, b, c, 0, 0, 0); }
; __device__ __forceinline__ void sub_C(const LAS unsigned char* cb, const bf16x8 (&qf)[4], int kq, int h, f32x16& o0, f32x16& o1, float& carry) {
;     ...
;     for (int s = 0; s < 4; ++s) z = mfma32(kf[s], qf[s], z);
;     f32x16 L;
; #pragma unroll
;     for (int i = 0; i < 16; ++i) { const float az = __builtin_fabsf(z[i]); const float sp = __builtin_fmaxf(z[i], 0.f) + lg2(1.0f + ex2(-az)); L[i] = (CIDX(i) < kq) ? -sp : 0.f; }
; #pragma unroll
;     for (int i = 6; i >= 0; --i) { L[i] += L[i + 1]; L[8 + i] += L[8 + i + 1]; }
;     const float Tlo = L[0], Thi = L[8], Tlo_o = __shfl_xor(Tlo, 32), Thi_o = __shfl_xor(Thi, 32);
;     const float off_hi = carry + (h ? 0.f : Thi_o);
;     const float off_lo = carry + Thi + Thi_o + (h ? 0.f : Tlo_o);
;     carry += (Tlo + Thi) + (Tlo_o + Thi_o);
; #pragma unroll
;     for (int i = 0; i < 16; ++i) { const float la = z[i] + L[i] + (i < 8 ? off_lo : off_hi); z[i] = (CIDX(i) < kq) ? ex2(la) : 0.f; }
	s_waitcnt lgkmcnt(4)
	v_mfma_f32_32x32x16_bf16 v[48:63], v[146:149], v[72:75], v[48:63]
	v_cndmask_b32_e32 v3, 64, v202, vcc
	v_cmp_lt_i32_e64 s[58:59], 0, v3
	v_cmp_lt_i32_e32 vcc, 1, v3
	v_cmp_lt_i32_e64 s[74:75], 22, v3
	v_cmp_lt_i32_e64 s[78:79], 23, v3
	v_cmp_lt_i32_e64 s[0:1], 2, v3
	v_cmp_lt_i32_e64 s[70:71], 21, v3
	v_mfma_f32_32x32x16_bf16 v[48:63], v[150:153], v[76:79], v[48:63]
	v_cmp_lt_i32_e64 s[76:77], 20, v3
	v_cmp_lt_i32_e64 s[72:73], 19, v3
	v_cmp_lt_i32_e64 s[60:61], 5, v3
	v_cmp_lt_i32_e64 s[68:69], 18, v3
	v_cmp_lt_i32_e64 s[64:65], 17, v3
	v_cmp_lt_i32_e64 s[66:67], 16, v3
	v_cmp_lt_i32_e64 s[62:63], 6, v3
	s_nop 4
	v_exp_f32_e64 v4, -|v48|
	v_exp_f32_e64 v6, -|v49|
	v_exp_f32_e64 v8, -|v50|
	v_exp_f32_e64 v12, -|v52|
	v_add_f32_e32 v4, 1.0, v4
	v_add_f32_e32 v6, 1.0, v6
	v_add_f32_e32 v8, 1.0, v8
	v_add_f32_e32 v12, 1.0, v12
	v_log_f32_e32 v4, v4
	v_log_f32_e32 v6, v6
	v_log_f32_e32 v8, v8
	v_log_f32_e32 v12, v12
	v_max_f32_e32 v2, v48, v48
	v_max_f32_e32 v5, v49, v49
	v_max_f32_e32 v7, v50, v50
	v_max_f32_e32 v11, v52, v52
	v_max_f32_e32 v2, 0, v2
	v_max_f32_e32 v5, 0, v5
	v_max_f32_e32 v7, 0, v7
	v_max_f32_e32 v11, 0, v11
	v_add_f32_e32 v2, v2, v4
	v_add_f32_e32 v4, v5, v6
	v_add_f32_e32 v5, v7, v8
	v_add_f32_e32 v7, v11, v12
	v_exp_f32_e64 v12, -|v56|
	v_exp_f32_e64 v13, -|v53|
	v_exp_f32_e64 v14, -|v57|
	v_cndmask_b32_e64 v8, 0, -v2, s[58:59]
	v_add_f32_e32 v12, 1.0, v12
	v_log_f32_e32 v12, v12
	v_add_f32_e32 v2, 1.0, v13
	v_max_f32_e32 v13, v56, v56
	v_max_f32_e32 v13, 0, v13
	v_add_f32_e32 v12, v13, v12
	v_add_f32_e32 v13, 1.0, v14
	v_log_f32_e32 v13, v13
	v_exp_f32_e64 v15, -|v58|
	v_max_f32_e32 v14, v57, v57
	v_max_f32_e32 v14, 0, v14
	v_add_f32_e32 v13, v14, v13
	v_add_f32_e32 v14, 1.0, v15
	v_log_f32_e32 v14, v14
	v_exp_f32_e64 v87, -|v59|
	v_max_f32_e32 v15, v58, v58
	v_max_f32_e32 v15, 0, v15
	v_add_f32_e32 v14, v15, v14
	v_add_f32_e32 v15, 1.0, v87
	v_log_f32_e32 v15, v15
	v_exp_f32_e64 v88, -|v60|
	v_max_f32_e32 v87, v59, v59
	v_max_f32_e32 v87, 0, v87
	v_add_f32_e32 v15, v87, v15
	v_add_f32_e32 v87, 1.0, v88
	v_log_f32_e32 v87, v87
	v_exp_f32_e64 v89, -|v61|
	v_max_f32_e32 v88, v60, v60
	v_max_f32_e32 v88, 0, v88
	v_add_f32_e32 v87, v88, v87
	v_add_f32_e32 v88, 1.0, v89
	v_log_f32_e32 v88, v88
	v_exp_f32_e64 v90, -|v62|
	v_exp_f32_e64 v10, -|v51|
	v_max_f32_e32 v89, v61, v61
	v_max_f32_e32 v89, 0, v89
	v_add_f32_e32 v88, v89, v88
	v_add_f32_e32 v89, 1.0, v90
	v_exp_f32_e64 v90, -|v63|
	v_add_f32_e32 v10, 1.0, v10
	v_log_f32_e32 v10, v10
	v_log_f32_e32 v89, v89
	v_add_f32_e32 v90, 1.0, v90
	v_max_f32_e32 v9, v51, v51
	v_max_f32_e32 v91, v62, v62
	v_log_f32_e32 v90, v90
	v_max_f32_e32 v9, 0, v9
	v_max_f32_e32 v91, 0, v91
	v_add_f32_e32 v6, v9, v10
	v_cndmask_b32_e64 v9, 0, -v4, vcc
	v_exp_f32_e64 v4, -|v54|
	v_add_f32_e32 v89, v91, v89
	v_max_f32_e32 v91, v63, v63
	v_max_f32_e32 v91, 0, v91
	v_log_f32_e32 v2, v2
	v_add_f32_e32 v90, v91, v90
	v_cndmask_b32_e64 v89, 0, -v89, s[74:75]
	v_cndmask_b32_e64 v91, 0, -v90, s[78:79]
	v_cndmask_b32_e64 v10, 0, -v5, s[0:1]
	v_max_f32_e32 v5, v53, v53
	v_add_f32_e32 v4, 1.0, v4
	v_cndmask_b32_e64 v88, 0, -v88, s[70:71]
	v_add_f32_e32 v91, v89, v91
	v_max_f32_e32 v5, 0, v5
	v_log_f32_e32 v4, v4
	v_cndmask_b32_e64 v87, 0, -v87, s[76:77]
	v_add_f32_e32 v92, v88, v91
	v_add_f32_e32 v2, v5, v2
	v_cndmask_b32_e64 v15, 0, -v15, s[72:73]
	v_add_f32_e32 v87, v87, v92
	v_cndmask_b32_e64 v11, 0, -v2, s[60:61]
	v_max_f32_e32 v2, v54, v54
	v_cndmask_b32_e64 v14, 0, -v14, s[68:69]
	v_add_f32_e32 v93, v15, v87
	v_max_f32_e32 v2, 0, v2
	v_cndmask_b32_e64 v13, 0, -v13, s[64:65]
	v_add_f32_e32 v94, v14, v93
	v_add_f32_e32 v2, v2, v4
	v_exp_f32_e64 v4, -|v55|
	v_cndmask_b32_e64 v12, 0, -v12, s[66:67]
	v_add_f32_e32 v13, v13, v94
	v_and_b32_e32 v14, 64, v236
	v_add_f32_e32 v15, v12, v13
	v_xor_b32_e32 v12, 32, v236
	v_add_u32_e32 v14, 64, v14
	v_cmp_lt_i32_e64 s[82:83], v12, v14
	v_add_f32_e32 v4, 1.0, v4
	v_log_f32_e32 v4, v4
	v_cndmask_b32_e64 v12, v236, v12, s[82:83]
	v_lshlrev_b32_e32 v12, 2, v12
	ds_bpermute_b32 v14, v12, v15
	v_max_f32_e32 v5, v55, v55
	v_max_f32_e32 v5, 0, v5
	v_add_f32_e32 v95, v5, v4
	v_cmp_lt_i32_e64 s[82:83], 7, v3
	v_cmp_lt_i32_e64 s[54:55], 3, v3
	v_cmp_lt_i32_e64 s[56:57], 4, v3
	v_cndmask_b32_e64 v2, 0, -v2, s[62:63]
	v_cndmask_b32_e64 v4, 0, -v95, s[82:83]
	v_add_f32_e32 v3, v86, v15
	s_waitcnt lgkmcnt(0)
	v_mov_b32_e32 v5, v14
	v_pk_add_f32 v[2:3], v[2:3], v[4:5]
	v_cndmask_b32_e64 v7, 0, -v7, s[56:57]
	v_add_f32_e32 v96, v11, v2
	v_cndmask_b32_e64 v6, 0, -v6, s[54:55]
	v_add_f32_e32 v97, v7, v96
	v_add_f32_e32 v98, v6, v97
	v_add_f32_e32 v99, v10, v98
	v_add_f32_e32 v100, v9, v99
	v_add_f32_e32 v89, v8, v100
	ds_bpermute_b32 v88, v12, v89
	v_mov_b32_e32 v4, v54
	v_add_f32_e32 v6, v48, v89
	v_cndmask_b32_e64 v48, 0, v14, s[38:39]
	v_add_f32_e32 v48, v86, v48
	s_waitcnt lgkmcnt(0)
	v_cndmask_b32_e64 v5, 0, v88, s[38:39]
	v_pk_add_f32 v[10:11], v[4:5], v[2:3]
	v_add_f32_e32 v49, v49, v100
	v_add_f32_e32 v10, v10, v11
	v_exp_f32_e32 v10, v10
	v_add_f32_e32 v50, v50, v99
	v_add_f32_e32 v51, v51, v98
	v_add_f32_e32 v52, v52, v97
	v_add_f32_e32 v53, v53, v96
	v_sub_f32_e32 v54, v55, v95
	v_cndmask_b32_e64 v55, 0, v10, s[62:63]
	v_add_f32_e32 v10, v57, v13
	v_add_f32_e32 v2, v6, v11
	v_add_f32_e32 v49, v49, v11
	v_add_f32_e32 v50, v50, v11
	v_add_f32_e32 v51, v51, v11
	v_add_f32_e32 v52, v52, v11
	v_add_f32_e32 v53, v53, v11
	v_add_f32_e32 v11, v54, v11
	v_add_f32_e32 v10, v48, v10
	v_exp_f32_e32 v11, v11
	v_exp_f32_e32 v10, v10
	v_add_f32_e32 v54, v56, v15
	v_add_f32_e32 v13, v59, v93
	v_cndmask_b32_e64 v56, 0, v11, s[82:83]
	v_add_f32_e32 v11, v58, v94
	v_cndmask_b32_e64 v58, 0, v10, s[64:65]
	v_add_f32_e32 v10, v61, v92
	v_exp_f32_e32 v12, v2
	v_exp_f32_e32 v49, v49
	v_exp_f32_e32 v50, v50
	v_exp_f32_e32 v51, v51
	v_exp_f32_e32 v52, v52
	v_exp_f32_e32 v53, v53
	v_add_f32_e32 v11, v48, v11
	v_add_f32_e32 v13, v48, v13
	v_add_f32_e32 v10, v48, v10
	v_exp_f32_e32 v11, v11
	v_exp_f32_e32 v13, v13
	v_exp_f32_e32 v61, v10
	v_add_f32_e32 v10, v62, v91


; __device__ __forceinline__ float ex2(float x) { return __builtin_amdgcn_exp2f(x); }
; __device__ __forceinline__ f32x16 mfma32(bf16x8 a, bf16x8 b, f32x16 c) { return __builtin_amdgcn_mfma_f32_32x32x16_bf16(a, b, c, 0, 0, 0); }
; __device__ __forceinline__ void sub_C(const LAS unsigned char* cb, const bf16x8 (&qf)[4], int kq, int h, f32x16& o0, f32x16& o1, float& carry) {
;     ...
;     for (int i = 0; i < 16; ++i) { const float la = z[i] + L[i] + (i < 8 ? off_lo : off_hi); z[i] = (CIDX(i) < kq) ? ex2(la) : 0.f; }
;     bf16x8 p0, p1; pack_p(z, p0, p1);
;     o0 = mfma32(vf[0][0], p0, o0); o0 = mfma32(vf[0][1], p1, o0);
;     o1 = mfma32(vf[1][0], p0, o1); o1 = mfma32(vf[1][1], p1, o1);
	v_add_f32_e32 v10, v48, v10
	v_exp_f32_e32 v62, v10
	v_sub_f32_e32 v10, v63, v90
	v_cndmask_b32_e64 v12, 0, v12, s[58:59]
	v_cndmask_b32_e32 v49, 0, v49, vcc
	v_cndmask_b32_e64 v50, 0, v50, s[0:1]
	v_cndmask_b32_e64 v51, 0, v51, s[54:55]
	v_cndmask_b32_e64 v52, 0, v52, s[56:57]
	v_cndmask_b32_e64 v53, 0, v53, s[60:61]
	v_add_f32_e32 v57, v60, v87
	v_add_f32_e32 v10, v10, v48
	v_add_f32_e32 v54, v48, v54
	v_add_f32_e32 v57, v48, v57
	v_cndmask_b32_e64 v59, 0, v11, s[68:69]
	v_cndmask_b32_e64 v60, 0, v13, s[72:73]
	v_exp_f32_e32 v48, v10
	v_cvt_pk_bf16_f32 v10, v12, v49
	v_cvt_pk_bf16_f32 v11, v50, v51
	v_cvt_pk_bf16_f32 v12, v52, v53
	v_cvt_pk_bf16_f32 v13, v55, v56
	v_exp_f32_e32 v54, v54
	v_exp_f32_e32 v57, v57
	s_waitcnt lgkmcnt(0)
	v_mfma_f32_32x32x16_bf16 v[32:47], v[154:157], v[10:13], v[32:47]
	v_cndmask_b32_e64 v4, 0, v61, s[70:71]
	v_cndmask_b32_e64 v54, 0, v54, s[66:67]
	v_cndmask_b32_e64 v57, 0, v57, s[76:77]
	v_cndmask_b32_e64 v5, 0, v62, s[74:75]
	v_cndmask_b32_e64 v48, 0, v48, s[78:79]
	v_cvt_pk_bf16_f32 v2, v54, v58
	v_cvt_pk_bf16_f32 v3, v59, v60
	v_cvt_pk_bf16_f32 v4, v57, v4
	v_cvt_pk_bf16_f32 v5, v5, v48
	s_nop 1
	v_mfma_f32_32x32x16_bf16 v[32:47], v[158:161], v[2:5], v[32:47]


; #define LAS __attribute__((address_space(3)))
; __device__ __forceinline__ f32x16 mfma32(bf16x8 a, bf16x8 b, f32x16 c) { return __builtin_amdgcn_mfma_f32_32x32x16_bf16(a, b, c, 0, 0, 0); }
; #define FRAG_LOAD(cb_) do { LOADK(kf, cb_); LOADV(vf, cb_); } while (0)
; __device__ __forceinline__ void sub_C(const LAS unsigned char* cb, const bf16x8 (&qf)[4], int kq, int h, f32x16& o0, f32x16& o1, float& carry) {
;     bf16x8 kf[4], vf[2][2]; FRAG_LOAD(cb);
;     f32x16 z = {};
; #pragma unroll
;     for (int s = 0; s < 4; ++s) z = mfma32(kf[s], qf[s], z);
;     ...
;     o0 = mfma32(vf[0][0], p0, o0); o0 = mfma32(vf[0][1], p1, o0);
;     o1 = mfma32(vf[1][0], p0, o1); o1 = mfma32(vf[1][1], p1, o1);
	v_mfma_f32_32x32x16_bf16 v[16:31], v[162:165], v[10:13], v[16:31]
	v_add_f32_e64 v6, v88, v14
	v_add_f32_e64 v7, v89, v15
	v_add_f32_e32 v6, v6, v7
	v_add_f32_e32 v86, v86, v6
	v_cmp_gt_f32_e32 vcc, s20, v86
	s_cmp_eq_u64 vcc, exec
	s_cselect_b64 s[0:1], -1, 0
	v_mfma_f32_32x32x16_bf16 v[16:31], v[166:169], v[2:5], v[16:31]
.LBB0_324:
	s_cmp_gt_i32 s52, s29
	s_cselect_b64 s[54:55], -1, 0
	s_or_b64 s[54:55], s[54:55], s[0:1]
	s_and_b64 vcc, exec, s[54:55]
	s_cbranch_vccnz .LBB0_330
	ds_read_b128 v[2:5], v0 offset:35072
	ds_read_b128 v[6:9], v0 offset:36096
	ds_read_b128 v[146:149], v0 offset:37120
	ds_read_b128 v[150:153], v0 offset:38144
	ds_read_b128 v[154:157], v0 offset:39168
	ds_read_b128 v[158:161], v0 offset:40192
	ds_read_b128 v[162:165], v0 offset:41216
	ds_read_b128 v[166:169], v0 offset:42240
	s_cmp_eq_u32 s27, 1
	s_cselect_b64 vcc, -1, 0
	s_waitcnt lgkmcnt(6)
	v_mfma_f32_32x32x16_bf16 v[48:63], v[2:5], v[64:67], 0
	v_mfma_f32_32x32x16_bf16 v[48:63], v[6:9], v[68:71], v[48:63]


; __device__ __forceinline__ float ex2(float x) { return __builtin_amdgcn_exp2f(x); }
; __device__ __forceinline__ float lg2(float x) { return __builtin_amdgcn_logf(x); }
; __device__ __forceinline__ f32x16 mfma32(bf16x8 a, bf16x8 b, f32x16 c) { return __builtin_amdgcn_mfma_f32_32x32x16_bf16(a, b, c, 0, 0, 0); }
; __device__ __forceinline__ void sub_C(const LAS unsigned char* cb, const bf16x8 (&qf)[4], int kq, int h, f32x16& o0, f32x16& o1, float& carry) {
;     ...
;     for (int s = 0; s < 4; ++s) z = mfma32(kf[s], qf[s], z);
;     f32x16 L;
; #pragma unroll
;     for (int i = 0; i < 16; ++i) { const float az = __builtin_fabsf(z[i]); const float sp = __builtin_fmaxf(z[i], 0.f) + lg2(1.0f + ex2(-az)); L[i] = (CIDX(i) < kq) ? -sp : 0.f; }
; #pragma unroll
;     for (int i = 6; i >= 0; --i) { L[i] += L[i + 1]; L[8 + i] += L[8 + i + 1]; }
;     const float Tlo = L[0], Thi = L[8], Tlo_o = __shfl_xor(Tlo, 32), Thi_o = __shfl_xor(Thi, 32);
;     const float off_hi = carry + (h ? 0.f : Thi_o);
;     const float off_lo = carry + Thi + Thi_o + (h ? 0.f : Tlo_o);
;     carry += (Tlo + Thi) + (Tlo_o + Thi_o);
; #pragma unroll
;     for (int i = 0; i < 16; ++i) { const float la = z[i] + L[i] + (i < 8 ? off_lo : off_hi); z[i] = (CIDX(i) < kq) ? ex2(la) : 0.f; }
	s_waitcnt lgkmcnt(4)
	v_mfma_f32_32x32x16_bf16 v[48:63], v[146:149], v[72:75], v[48:63]
	v_cndmask_b32_e32 v3, 64, v202, vcc
	v_cmp_lt_i32_e64 s[58:59], 0, v3
	v_cmp_lt_i32_e32 vcc, 1, v3
	v_cmp_lt_i32_e64 s[74:75], 22, v3
	v_cmp_lt_i32_e64 s[78:79], 23, v3
	v_cmp_lt_i32_e64 s[0:1], 2, v3
	v_cmp_lt_i32_e64 s[70:71], 21, v3
	v_mfma_f32_32x32x16_bf16 v[48:63], v[150:153], v[76:79], v[48:63]
	v_cmp_lt_i32_e64 s[76:77], 20, v3
	v_cmp_lt_i32_e64 s[72:73], 19, v3
	v_cmp_lt_i32_e64 s[60:61], 5, v3
	v_cmp_lt_i32_e64 s[68:69], 18, v3
	v_cmp_lt_i32_e64 s[64:65], 17, v3
	v_cmp_lt_i32_e64 s[66:67], 16, v3
	v_cmp_lt_i32_e64 s[62:63], 6, v3
	s_nop 4
	v_exp_f32_e64 v4, -|v48|
	v_exp_f32_e64 v6, -|v49|
	v_exp_f32_e64 v8, -|v50|
	v_exp_f32_e64 v12, -|v52|
	v_add_f32_e32 v4, 1.0, v4
	v_add_f32_e32 v6, 1.0, v6
	v_add_f32_e32 v8, 1.0, v8
	v_add_f32_e32 v12, 1.0, v12
	v_log_f32_e32 v4, v4
	v_log_f32_e32 v6, v6
	v_log_f32_e32 v8, v8
	v_log_f32_e32 v12, v12
	v_max_f32_e32 v2, v48, v48
	v_max_f32_e32 v5, v49, v49
	v_max_f32_e32 v7, v50, v50
	v_max_f32_e32 v11, v52, v52
	v_max_f32_e32 v2, 0, v2
	v_max_f32_e32 v5, 0, v5
	v_max_f32_e32 v7, 0, v7
	v_max_f32_e32 v11, 0, v11
	v_add_f32_e32 v2, v2, v4
	v_add_f32_e32 v4, v5, v6
	v_add_f32_e32 v5, v7, v8
	v_add_f32_e32 v7, v11, v12
	v_exp_f32_e64 v12, -|v56|
	v_exp_f32_e64 v13, -|v53|
	v_exp_f32_e64 v14, -|v57|
	v_cndmask_b32_e64 v8, 0, -v2, s[58:59]
	v_add_f32_e32 v12, 1.0, v12
	v_log_f32_e32 v12, v12
	v_add_f32_e32 v2, 1.0, v13
	v_max_f32_e32 v13, v56, v56
	v_max_f32_e32 v13, 0, v13
	v_add_f32_e32 v12, v13, v12
	v_add_f32_e32 v13, 1.0, v14
	v_log_f32_e32 v13, v13
	v_exp_f32_e64 v15, -|v58|
	v_max_f32_e32 v14, v57, v57
	v_max_f32_e32 v14, 0, v14
	v_add_f32_e32 v13, v14, v13
	v_add_f32_e32 v14, 1.0, v15
	v_log_f32_e32 v14, v14
	v_exp_f32_e64 v87, -|v59|
	v_max_f32_e32 v15, v58, v58
	v_max_f32_e32 v15, 0, v15
	v_add_f32_e32 v14, v15, v14
	v_add_f32_e32 v15, 1.0, v87
	v_log_f32_e32 v15, v15
	v_exp_f32_e64 v88, -|v60|
	v_max_f32_e32 v87, v59, v59
	v_max_f32_e32 v87, 0, v87
	v_add_f32_e32 v15, v87, v15
	v_add_f32_e32 v87, 1.0, v88
	v_log_f32_e32 v87, v87
	v_exp_f32_e64 v89, -|v61|
	v_max_f32_e32 v88, v60, v60
	v_max_f32_e32 v88, 0, v88
	v_add_f32_e32 v87, v88, v87
	v_add_f32_e32 v88, 1.0, v89
	v_log_f32_e32 v88, v88
	v_exp_f32_e64 v90, -|v62|
	v_exp_f32_e64 v10, -|v51|
	v_max_f32_e32 v89, v61, v61
	v_max_f32_e32 v89, 0, v89
	v_add_f32_e32 v88, v89, v88
	v_add_f32_e32 v89, 1.0, v90
	v_exp_f32_e64 v90, -|v63|
	v_add_f32_e32 v10, 1.0, v10
	v_log_f32_e32 v10, v10
	v_log_f32_e32 v89, v89
	v_add_f32_e32 v90, 1.0, v90
	v_max_f32_e32 v9, v51, v51
	v_max_f32_e32 v91, v62, v62
	v_log_f32_e32 v90, v90
	v_max_f32_e32 v9, 0, v9
	v_max_f32_e32 v91, 0, v91
	v_add_f32_e32 v6, v9, v10
	v_cndmask_b32_e64 v9, 0, -v4, vcc
	v_exp_f32_e64 v4, -|v54|
	v_add_f32_e32 v89, v91, v89
	v_max_f32_e32 v91, v63, v63
	v_max_f32_e32 v91, 0, v91
	v_log_f32_e32 v2, v2
	v_add_f32_e32 v90, v91, v90
	v_cndmask_b32_e64 v89, 0, -v89, s[74:75]
	v_cndmask_b32_e64 v91, 0, -v90, s[78:79]
	v_cndmask_b32_e64 v10, 0, -v5, s[0:1]
	v_max_f32_e32 v5, v53, v53
	v_add_f32_e32 v4, 1.0, v4
	v_cndmask_b32_e64 v88, 0, -v88, s[70:71]
	v_add_f32_e32 v91, v89, v91
	v_max_f32_e32 v5, 0, v5
	v_log_f32_e32 v4, v4
	v_cndmask_b32_e64 v87, 0, -v87, s[76:77]
	v_add_f32_e32 v92, v88, v91
	v_add_f32_e32 v2, v5, v2
	v_cndmask_b32_e64 v15, 0, -v15, s[72:73]
	v_add_f32_e32 v87, v87, v92
	v_cndmask_b32_e64 v11, 0, -v2, s[60:61]
	v_max_f32_e32 v2, v54, v54
	v_cndmask_b32_e64 v14, 0, -v14, s[68:69]
	v_add_f32_e32 v93, v15, v87
	v_max_f32_e32 v2, 0, v2
	v_cndmask_b32_e64 v13, 0, -v13, s[64:65]
	v_add_f32_e32 v94, v14, v93
	v_add_f32_e32 v2, v2, v4
	v_exp_f32_e64 v4, -|v55|
	v_cndmask_b32_e64 v12, 0, -v12, s[66:67]
	v_add_f32_e32 v13, v13, v94
	v_and_b32_e32 v14, 64, v236
	v_add_f32_e32 v15, v12, v13
	v_xor_b32_e32 v12, 32, v236
	v_add_u32_e32 v14, 64, v14
	v_cmp_lt_i32_e64 s[82:83], v12, v14
	v_add_f32_e32 v4, 1.0, v4
	v_log_f32_e32 v4, v4
	v_cndmask_b32_e64 v12, v236, v12, s[82:83]
	v_lshlrev_b32_e32 v12, 2, v12
	ds_bpermute_b32 v14, v12, v15
	v_max_f32_e32 v5, v55, v55
	v_max_f32_e32 v5, 0, v5
	v_add_f32_e32 v95, v5, v4
	v_cmp_lt_i32_e64 s[82:83], 7, v3
	v_cmp_lt_i32_e64 s[54:55], 3, v3
	v_cmp_lt_i32_e64 s[56:57], 4, v3
	v_cndmask_b32_e64 v2, 0, -v2, s[62:63]
	v_cndmask_b32_e64 v4, 0, -v95, s[82:83]
	v_add_f32_e32 v3, v86, v15
	s_waitcnt lgkmcnt(0)
	v_mov_b32_e32 v5, v14
	v_pk_add_f32 v[2:3], v[2:3], v[4:5]
	v_cndmask_b32_e64 v7, 0, -v7, s[56:57]
	v_add_f32_e32 v96, v11, v2
	v_cndmask_b32_e64 v6, 0, -v6, s[54:55]
	v_add_f32_e32 v97, v7, v96
	v_add_f32_e32 v98, v6, v97
	v_add_f32_e32 v99, v10, v98
	v_add_f32_e32 v100, v9, v99
	v_add_f32_e32 v89, v8, v100
	ds_bpermute_b32 v88, v12, v89
	v_mov_b32_e32 v4, v54
	v_add_f32_e32 v6, v48, v89
	v_cndmask_b32_e64 v48, 0, v14, s[38:39]
	v_add_f32_e32 v48, v86, v48
	s_waitcnt lgkmcnt(0)
	v_cndmask_b32_e64 v5, 0, v88, s[38:39]
	v_pk_add_f32 v[10:11], v[4:5], v[2:3]
	v_add_f32_e32 v49, v49, v100
	v_add_f32_e32 v10, v10, v11
	v_exp_f32_e32 v10, v10
	v_add_f32_e32 v50, v50, v99
	v_add_f32_e32 v51, v51, v98
	v_add_f32_e32 v52, v52, v97
	v_add_f32_e32 v53, v53, v96
	v_sub_f32_e32 v54, v55, v95
	v_cndmask_b32_e64 v55, 0, v10, s[62:63]
	v_add_f32_e32 v10, v57, v13
	v_add_f32_e32 v2, v6, v11
	v_add_f32_e32 v49, v49, v11
	v_add_f32_e32 v50, v50, v11
	v_add_f32_e32 v51, v51, v11
	v_add_f32_e32 v52, v52, v11
	v_add_f32_e32 v53, v53, v11
	v_add_f32_e32 v11, v54, v11
	v_add_f32_e32 v10, v48, v10
	v_exp_f32_e32 v11, v11
	v_exp_f32_e32 v10, v10
	v_add_f32_e32 v54, v56, v15
	v_add_f32_e32 v13, v59, v93
	v_cndmask_b32_e64 v56, 0, v11, s[82:83]
	v_add_f32_e32 v11, v58, v94
	v_cndmask_b32_e64 v58, 0, v10, s[64:65]
	v_add_f32_e32 v10, v61, v92
	v_exp_f32_e32 v12, v2
	v_exp_f32_e32 v49, v49
	v_exp_f32_e32 v50, v50
	v_exp_f32_e32 v51, v51
	v_exp_f32_e32 v52, v52
	v_exp_f32_e32 v53, v53
	v_add_f32_e32 v11, v48, v11
	v_add_f32_e32 v13, v48, v13
	v_add_f32_e32 v10, v48, v10
	v_exp_f32_e32 v11, v11
	v_exp_f32_e32 v13, v13
	v_exp_f32_e32 v61, v10
	v_add_f32_e32 v10, v62, v91


; __device__ __forceinline__ float ex2(float x) { return __builtin_amdgcn_exp2f(x); }
; __device__ __forceinline__ f32x16 mfma32(bf16x8 a, bf16x8 b, f32x16 c) { return __builtin_amdgcn_mfma_f32_32x32x16_bf16(a, b, c, 0, 0, 0); }
; __device__ __forceinline__ void sub_C(const LAS unsigned char* cb, const bf16x8 (&qf)[4], int kq, int h, f32x16& o0, f32x16& o1, float& carry) {
;     ...
;     for (int i = 0; i < 16; ++i) { const float la = z[i] + L[i] + (i < 8 ? off_lo : off_hi); z[i] = (CIDX(i) < kq) ? ex2(la) : 0.f; }
;     bf16x8 p0, p1; pack_p(z, p0, p1);
;     o0 = mfma32(vf[0][0], p0, o0); o0 = mfma32(vf[0][1], p1, o0);
;     o1 = mfma32(vf[1][0], p0, o1); o1 = mfma32(vf[1][1], p1, o1);
	v_add_f32_e32 v10, v48, v10
	v_exp_f32_e32 v62, v10
	v_sub_f32_e32 v10, v63, v90
	v_cndmask_b32_e64 v12, 0, v12, s[58:59]
	v_cndmask_b32_e32 v49, 0, v49, vcc
	v_cndmask_b32_e64 v50, 0, v50, s[0:1]
	v_cndmask_b32_e64 v51, 0, v51, s[54:55]
	v_cndmask_b32_e64 v52, 0, v52, s[56:57]
	v_cndmask_b32_e64 v53, 0, v53, s[60:61]
	v_add_f32_e32 v57, v60, v87
	v_add_f32_e32 v10, v10, v48
	v_add_f32_e32 v54, v48, v54
	v_add_f32_e32 v57, v48, v57
	v_cndmask_b32_e64 v59, 0, v11, s[68:69]
	v_cndmask_b32_e64 v60, 0, v13, s[72:73]
	v_exp_f32_e32 v48, v10
	v_cvt_pk_bf16_f32 v10, v12, v49
	v_cvt_pk_bf16_f32 v11, v50, v51
	v_cvt_pk_bf16_f32 v12, v52, v53
	v_cvt_pk_bf16_f32 v13, v55, v56
	v_exp_f32_e32 v54, v54
	v_exp_f32_e32 v57, v57
	s_waitcnt lgkmcnt(0)
	v_mfma_f32_32x32x16_bf16 v[32:47], v[154:157], v[10:13], v[32:47]
	v_cndmask_b32_e64 v4, 0, v61, s[70:71]
	v_cndmask_b32_e64 v54, 0, v54, s[66:67]
	v_cndmask_b32_e64 v57, 0, v57, s[76:77]
	v_cndmask_b32_e64 v5, 0, v62, s[74:75]
	v_cndmask_b32_e64 v48, 0, v48, s[78:79]
	v_cvt_pk_bf16_f32 v2, v54, v58
	v_cvt_pk_bf16_f32 v3, v59, v60
	v_cvt_pk_bf16_f32 v4, v57, v4
	v_cvt_pk_bf16_f32 v5, v5, v48
	s_nop 1
	v_mfma_f32_32x32x16_bf16 v[32:47], v[158:161], v[2:5], v[32:47]


; __device__ __forceinline__ f32x16 mfma32(bf16x8 a, bf16x8 b, f32x16 c) { return __builtin_amdgcn_mfma_f32_32x32x16_bf16(a, b, c, 0, 0, 0); }
; __device__ __forceinline__ void sub_C(const LAS unsigned char* cb, const bf16x8 (&qf)[4], int kq, int h, f32x16& o0, f32x16& o1, float& carry) {
;     ...
;     o0 = mfma32(vf[0][0], p0, o0); o0 = mfma32(vf[0][1], p1, o0);
;     o1 = mfma32(vf[1][0], p0, o1); o1 = mfma32(vf[1][1], p1, o1);
; __device__ __forceinline__ void blk_C(int b, int hd, int chunk, const bf16_t* QK, const bf16_t* VT, bf16_t* mixed, LAS unsigned char* lds, int tid, int lane, int wave) {
;     ...
;             if (kb <= qb && !done) { sub_C(cb + u * 8192, qf, (kb == qb) ? q - 8 * h : 64, h, o0, o1, carry); if (__all(carry < -64.0f)) done = true; } }
;         if (lane == 0) flags[(step & 1) * 8 + wave] = (more && !done) ? 1u : 0u;
	v_mfma_f32_32x32x16_bf16 v[16:31], v[162:165], v[10:13], v[16:31]
	v_add_f32_e64 v6, v88, v14
	v_add_f32_e64 v7, v89, v15
	v_add_f32_e32 v0, v6, v7
	v_add_f32_e32 v86, v86, v0
	v_cmp_gt_f32_e32 vcc, s20, v86
	s_cmp_eq_u64 vcc, exec
	s_cselect_b64 s[0:1], -1, 0
	v_mfma_f32_32x32x16_bf16 v[16:31], v[166:169], v[2:5], v[16:31]
	s_and_saveexec_b64 s[54:55], s[40:41]
	s_xor_b64 s[54:55], exec, s[54:55]
	s_cbranch_execnz .LBB0_331

; #define WAITBAR2() asm volatile("s_waitcnt vmcnt(2) lgkmcnt(0)\n\ts_barrier" ::: "memory")
; __device__ __forceinline__ void blk_C(int b, int hd, int chunk, const bf16_t* QK, const bf16_t* VT, bf16_t* mixed, LAS unsigned char* lds, int tid, int lane, int wave) {
;     ...
;         if (lane == 0) flags[(step & 1) * 8 + wave] = (more && !done) ? 1u : 0u;
;         WAITBAR2();
;         slot_c = slot_c == NSTG - 1 ? 0 : slot_c + 1;
;         unsigned any = 0;
; #pragma unroll
;         for (int w = 0; w < 8; ++w) any |= flags[(step & 1) * 8 + w];
;         if (!any) break;
.LBB0_328:
	s_or_b64 exec, exec, s[54:55]
	v_lshl_add_u32 v0, v0, 2, 0
	s_waitcnt vmcnt(2) lgkmcnt(0)
	s_barrier
	v_add_u32_e32 v0, 0x20040, v0
	ds_read_b128 v[2:5], v0
	ds_read_b128 v[6:9], v0 offset:16
	s_mov_b64 s[54:55], -1
	s_waitcnt lgkmcnt(0)
	v_or3_b32 v2, v2, v3, v4
	v_or3_b32 v6, v5, v6, v7
	v_or3_b32 v0, v2, v6, v8
	v_or_b32_e32 v0, v0, v9
	v_cmp_ne_u32_e32 vcc, 0, v0
	s_and_saveexec_b64 s[56:57], vcc
	s_cbranch_execz .LBB0_321
	s_add_i32 s54, s35, 1
	s_cmp_lg_u32 s35, 2
	s_cselect_b32 s35, s54, 0
	s_add_i32 s54, s95, 1
	s_cmp_lg_u32 s95, 2
	s_cselect_b32 s95, s54, 0
	s_add_i32 s31, s31, -1
	s_add_i32 s27, s27, -2
	s_add_i32 s52, s52, -2
	s_add_i32 s53, s53, 8
	s_xor_b64 s[54:55], exec, -1
	s_branch .LBB0_321
